# v65 + non-leader barrier acquire (buffer_inv sc1) issued before the XGEN poll instead of after it
# baseline (speedup 1.0000x reference)
.LBB0_186:
	global_atomic_add v4, v187, v237, s[60:61] sc0
	v_cvt_f32_u32_e32 v1, v3
	v_sub_u32_e32 v5, 0, v3
	v_rcp_iflag_f32_e32 v1, v1
	s_nop 0
	v_mul_f32_e32 v1, 0x4f7ffffe, v1
	v_cvt_u32_f32_e32 v1, v1
	v_mul_lo_u32 v5, v5, v1
	v_mul_hi_u32 v5, v1, v5
	v_add_u32_e32 v1, v1, v5
	s_waitcnt vmcnt(0)
	v_mul_hi_u32 v1, v4, v1
	v_mul_lo_u32 v5, v1, v3
	v_sub_u32_e32 v5, v4, v5
	v_add_u32_e32 v6, 1, v1
	v_cmp_ge_u32_e32 vcc, v5, v3
	v_add_u32_e32 v4, 1, v4
	s_nop 0
	v_cndmask_b32_e32 v1, v1, v6, vcc
	v_sub_u32_e32 v6, v5, v3
	v_cndmask_b32_e32 v5, v5, v6, vcc
	v_add_u32_e32 v6, 1, v1
	v_cmp_ge_u32_e32 vcc, v5, v3
	s_nop 1
	v_cndmask_b32_e32 v1, v1, v6, vcc
	v_mul_lo_u32 v5, v3, v1
	v_add_u32_e32 v3, v5, v3
	v_cmp_ne_u32_e32 vcc, v4, v3
	s_and_saveexec_b64 s[8:9], vcc
	s_xor_b64 s[8:9], exec, s[8:9]
	s_cbranch_execz .LBB0_200
	s_waitcnt lgkmcnt(0)
	buffer_inv sc1
	global_load_dword v2, v187, s[62:63] sc1
	s_waitcnt vmcnt(0)
	v_cmp_eq_u32_e32 vcc, v2, v1
	s_and_saveexec_b64 s[10:11], vcc
	s_cbranch_execz .LBB0_199
	s_mov_b32 s3, 1
	s_mov_b64 s[12:13], 0
	s_branch .LBB0_190

.LBB0_199:
	s_or_b64 exec, exec, s[10:11]
	s_waitcnt vmcnt(0)
	s_waitcnt vmcnt(0)

.LBB0_302:
	global_atomic_add v4, v187, v237, s[60:61] sc0
	v_cvt_f32_u32_e32 v1, v3
	v_sub_u32_e32 v5, 0, v3
	v_rcp_iflag_f32_e32 v1, v1
	s_nop 0
	v_mul_f32_e32 v1, 0x4f7ffffe, v1
	v_cvt_u32_f32_e32 v1, v1
	v_mul_lo_u32 v5, v5, v1
	v_mul_hi_u32 v5, v1, v5
	v_add_u32_e32 v1, v1, v5
	s_waitcnt vmcnt(0)
	v_mul_hi_u32 v1, v4, v1
	v_mul_lo_u32 v5, v1, v3
	v_sub_u32_e32 v5, v4, v5
	v_add_u32_e32 v6, 1, v1
	v_cmp_ge_u32_e32 vcc, v5, v3
	v_add_u32_e32 v4, 1, v4
	s_nop 0
	v_cndmask_b32_e32 v1, v1, v6, vcc
	v_sub_u32_e32 v6, v5, v3
	v_cndmask_b32_e32 v5, v5, v6, vcc
	v_add_u32_e32 v6, 1, v1
	v_cmp_ge_u32_e32 vcc, v5, v3
	s_nop 1
	v_cndmask_b32_e32 v1, v1, v6, vcc
	v_mul_lo_u32 v5, v3, v1
	v_add_u32_e32 v3, v5, v3
	v_cmp_ne_u32_e32 vcc, v4, v3
	s_and_saveexec_b64 s[14:15], vcc
	s_xor_b64 s[14:15], exec, s[14:15]
	s_cbranch_execz .LBB0_331
	s_waitcnt lgkmcnt(0)
	buffer_inv sc1
	global_load_dword v2, v187, s[62:63] sc1
	s_waitcnt vmcnt(0)
	v_cmp_eq_u32_e32 vcc, v2, v1
	s_and_saveexec_b64 s[16:17], vcc
	s_cbranch_execz .LBB0_330
	s_mov_b32 s3, 1
	s_mov_b64 s[18:19], 0
	s_branch .LBB0_306

.LBB0_317:
	global_atomic_add v4, v187, v237, s[60:61] sc0
	v_cvt_f32_u32_e32 v1, v3
	v_sub_u32_e32 v5, 0, v3
	v_rcp_iflag_f32_e32 v1, v1
	s_nop 0
	v_mul_f32_e32 v1, 0x4f7ffffe, v1
	v_cvt_u32_f32_e32 v1, v1
	v_mul_lo_u32 v5, v5, v1
	v_mul_hi_u32 v5, v1, v5
	v_add_u32_e32 v1, v1, v5
	s_waitcnt vmcnt(0)
	v_mul_hi_u32 v1, v4, v1
	v_mul_lo_u32 v5, v1, v3
	v_sub_u32_e32 v5, v4, v5
	v_add_u32_e32 v6, 1, v1
	v_cmp_ge_u32_e32 vcc, v5, v3
	v_add_u32_e32 v4, 1, v4
	s_nop 0
	v_cndmask_b32_e32 v1, v1, v6, vcc
	v_sub_u32_e32 v6, v5, v3
	v_cndmask_b32_e32 v5, v5, v6, vcc
	v_add_u32_e32 v6, 1, v1
	v_cmp_ge_u32_e32 vcc, v5, v3
	s_nop 1
	v_cndmask_b32_e32 v1, v1, v6, vcc
	v_mul_lo_u32 v5, v3, v1
	v_add_u32_e32 v3, v5, v3
	v_cmp_ne_u32_e32 vcc, v4, v3
	s_and_saveexec_b64 s[10:11], vcc
	s_xor_b64 s[10:11], exec, s[10:11]
	s_cbranch_execz .LBB0_348
	s_waitcnt lgkmcnt(0)
	buffer_inv sc1
	global_load_dword v2, v187, s[62:63] sc1
	s_waitcnt vmcnt(0)
	v_cmp_eq_u32_e32 vcc, v2, v1
	s_and_saveexec_b64 s[12:13], vcc
	s_cbranch_execz .LBB0_347
	s_mov_b32 s3, 1
	s_mov_b64 s[14:15], 0
	s_branch .LBB0_321

.LBB0_330:
	s_or_b64 exec, exec, s[16:17]
	s_waitcnt vmcnt(0)
	s_waitcnt vmcnt(0)

.LBB0_347:
	s_or_b64 exec, exec, s[12:13]
	s_waitcnt vmcnt(0)
	s_waitcnt vmcnt(0)

.LBB0_525:
	global_atomic_add v4, v187, v237, s[60:61] sc0
	v_cvt_f32_u32_e32 v1, v3
	v_sub_u32_e32 v5, 0, v3
	v_rcp_iflag_f32_e32 v1, v1
	s_nop 0
	v_mul_f32_e32 v1, 0x4f7ffffe, v1
	v_cvt_u32_f32_e32 v1, v1
	v_mul_lo_u32 v5, v5, v1
	v_mul_hi_u32 v5, v1, v5
	v_add_u32_e32 v1, v1, v5
	s_waitcnt vmcnt(0)
	v_mul_hi_u32 v1, v4, v1
	v_mul_lo_u32 v5, v1, v3
	v_sub_u32_e32 v5, v4, v5
	v_add_u32_e32 v6, 1, v1
	v_cmp_ge_u32_e32 vcc, v5, v3
	v_add_u32_e32 v4, 1, v4
	s_nop 0
	v_cndmask_b32_e32 v1, v1, v6, vcc
	v_sub_u32_e32 v6, v5, v3
	v_cndmask_b32_e32 v5, v5, v6, vcc
	v_add_u32_e32 v6, 1, v1
	v_cmp_ge_u32_e32 vcc, v5, v3
	s_nop 1
	v_cndmask_b32_e32 v1, v1, v6, vcc
	v_mul_lo_u32 v5, v3, v1
	v_add_u32_e32 v3, v5, v3
	v_cmp_ne_u32_e32 vcc, v4, v3
	s_and_saveexec_b64 s[6:7], vcc
	s_xor_b64 s[6:7], exec, s[6:7]
	s_cbranch_execz .LBB0_539
	s_waitcnt lgkmcnt(0)
	buffer_inv sc1
	global_load_dword v2, v187, s[62:63] sc1
	s_waitcnt vmcnt(0)
	v_cmp_eq_u32_e32 vcc, v2, v1
	s_and_saveexec_b64 s[10:11], vcc
	s_cbranch_execz .LBB0_538
	s_mov_b32 s3, 1
	s_mov_b64 s[12:13], 0
	s_branch .LBB0_529

.LBB0_701:
	global_atomic_add v4, v187, v237, s[60:61] sc0
	v_cvt_f32_u32_e32 v1, v3
	v_sub_u32_e32 v5, 0, v3
	v_rcp_iflag_f32_e32 v1, v1
	s_nop 0
	v_mul_f32_e32 v1, 0x4f7ffffe, v1
	v_cvt_u32_f32_e32 v1, v1
	v_mul_lo_u32 v5, v5, v1
	v_mul_hi_u32 v5, v1, v5
	v_add_u32_e32 v1, v1, v5
	s_waitcnt vmcnt(0)
	v_mul_hi_u32 v1, v4, v1
	v_mul_lo_u32 v5, v1, v3
	v_sub_u32_e32 v5, v4, v5
	v_add_u32_e32 v6, 1, v1
	v_cmp_ge_u32_e32 vcc, v5, v3
	v_add_u32_e32 v4, 1, v4
	s_nop 0
	v_cndmask_b32_e32 v1, v1, v6, vcc
	v_sub_u32_e32 v6, v5, v3
	v_cndmask_b32_e32 v5, v5, v6, vcc
	v_add_u32_e32 v6, 1, v1
	v_cmp_ge_u32_e32 vcc, v5, v3
	s_nop 1
	v_cndmask_b32_e32 v1, v1, v6, vcc
	v_mul_lo_u32 v5, v3, v1
	v_add_u32_e32 v3, v5, v3
	v_cmp_ne_u32_e32 vcc, v4, v3
	s_and_saveexec_b64 s[0:1], vcc
	s_xor_b64 s[6:7], exec, s[0:1]
	s_cbranch_execz .LBB0_715
	s_waitcnt lgkmcnt(0)
	buffer_inv sc1
	global_load_dword v2, v187, s[62:63] sc1
	s_waitcnt vmcnt(0)
	v_cmp_eq_u32_e32 vcc, v2, v1
	s_and_saveexec_b64 s[10:11], vcc
	s_cbranch_execz .LBB0_714
	s_mov_b32 s3, 1
	s_mov_b64 s[12:13], 0
	s_branch .LBB0_705

.LBB0_1073:
	global_atomic_add v4, v187, v237, s[60:61] sc0
	v_cvt_f32_u32_e32 v1, v3
	v_sub_u32_e32 v5, 0, v3
	v_rcp_iflag_f32_e32 v1, v1
	s_nop 0
	v_mul_f32_e32 v1, 0x4f7ffffe, v1
	v_cvt_u32_f32_e32 v1, v1
	v_mul_lo_u32 v5, v5, v1
	v_mul_hi_u32 v5, v1, v5
	v_add_u32_e32 v1, v1, v5
	s_waitcnt vmcnt(0)
	v_mul_hi_u32 v1, v4, v1
	v_mul_lo_u32 v5, v1, v3
	v_sub_u32_e32 v5, v4, v5
	v_add_u32_e32 v6, 1, v1
	v_cmp_ge_u32_e32 vcc, v5, v3
	v_add_u32_e32 v4, 1, v4
	s_nop 0
	v_cndmask_b32_e32 v1, v1, v6, vcc
	v_sub_u32_e32 v6, v5, v3
	v_cndmask_b32_e32 v5, v5, v6, vcc
	v_add_u32_e32 v6, 1, v1
	v_cmp_ge_u32_e32 vcc, v5, v3
	s_nop 1
	v_cndmask_b32_e32 v1, v1, v6, vcc
	v_mul_lo_u32 v5, v3, v1
	v_add_u32_e32 v3, v5, v3
	v_cmp_ne_u32_e32 vcc, v4, v3
	s_and_saveexec_b64 s[0:1], vcc
	s_xor_b64 s[8:9], exec, s[0:1]
	s_cbranch_execz .LBB0_1087
	s_waitcnt lgkmcnt(0)
	buffer_inv sc1
	global_load_dword v2, v187, s[62:63] sc1
	s_waitcnt vmcnt(0)
	v_cmp_eq_u32_e32 vcc, v2, v1
	s_and_saveexec_b64 s[10:11], vcc
	s_cbranch_execz .LBB0_1086
	s_mov_b32 s3, 1
	s_mov_b64 s[12:13], 0
	s_branch .LBB0_1077

.LBB0_1169:
	global_atomic_add v4, v187, v237, s[60:61] sc0
	v_cvt_f32_u32_e32 v1, v3
	v_sub_u32_e32 v5, 0, v3
	v_rcp_iflag_f32_e32 v1, v1
	s_nop 0
	v_mul_f32_e32 v1, 0x4f7ffffe, v1
	v_cvt_u32_f32_e32 v1, v1
	v_mul_lo_u32 v5, v5, v1
	v_mul_hi_u32 v5, v1, v5
	v_add_u32_e32 v1, v1, v5
	s_waitcnt vmcnt(0)
	v_mul_hi_u32 v1, v4, v1
	v_mul_lo_u32 v5, v1, v3
	v_sub_u32_e32 v5, v4, v5
	v_add_u32_e32 v6, 1, v1
	v_cmp_ge_u32_e32 vcc, v5, v3
	v_add_u32_e32 v4, 1, v4
	s_nop 0
	v_cndmask_b32_e32 v1, v1, v6, vcc
	v_sub_u32_e32 v6, v5, v3
	v_cndmask_b32_e32 v5, v5, v6, vcc
	v_add_u32_e32 v6, 1, v1
	v_cmp_ge_u32_e32 vcc, v5, v3
	s_nop 1
	v_cndmask_b32_e32 v1, v1, v6, vcc
	v_mul_lo_u32 v5, v3, v1
	v_add_u32_e32 v3, v5, v3
	v_cmp_ne_u32_e32 vcc, v4, v3
	s_and_saveexec_b64 s[0:1], vcc
	s_xor_b64 s[6:7], exec, s[0:1]
	s_cbranch_execz .LBB0_1183
	s_waitcnt lgkmcnt(0)
	buffer_inv sc1
	global_load_dword v2, v187, s[62:63] sc1
	s_waitcnt vmcnt(0)
	v_cmp_eq_u32_e32 vcc, v2, v1
	s_and_saveexec_b64 s[8:9], vcc
	s_cbranch_execz .LBB0_1182
	s_mov_b32 s2, 1
	s_mov_b64 s[10:11], 0
	s_branch .LBB0_1173

.LBB0_1182:
	s_or_b64 exec, exec, s[8:9]
	s_waitcnt vmcnt(0)
	s_waitcnt vmcnt(0)
